# merged GEMM + MLA loop: lane-invariant DMA address math hoisted out of the tile loop into free VGPRs, compact per-tile DMA block sunk below first QK MFMAs
# speedup vs baseline: 1.0142x; 1.0084x over previous
.LBB0_542:
	v_cndmask_b32_e64 v202, v50, v1, s[2:3]
	v_mul_f32_e32 v50, 0xbdd53b94, v202
	v_fmamk_f32 v35, v35, 0x3dd53b94, v50
	v_fmamk_f32 v34, v34, 0x3dd53b94, v50
	v_fmamk_f32 v36, v36, 0x3dd53b94, v50
	v_exp_f32_e32 v231, v35
	v_lshlrev_b32_e32 v35, 4, v161
	v_exp_f32_e32 v229, v34
	v_exp_f32_e32 v227, v36
	v_lshlrev_b32_e32 v34, 3, v161
	v_and_b32_e32 v35, 0xc0, v35
	v_lshlrev_b32_e32 v36, 1, v161
	v_and_or_b32 v35, v34, 24, v35
	v_and_b32_e32 v36, 32, v36
	v_and_b32_e32 v34, 0x100, v34
	s_cmp_lg_u32 0, -1
	v_fmamk_f32 v37, v37, 0x3dd53b94, v50
	v_fmamk_f32 v38, v38, 0x3dd53b94, v50
	v_fmamk_f32 v39, v39, 0x3dd53b94, v50
	v_fmamk_f32 v40, v40, 0x3dd53b94, v50
	v_fmamk_f32 v41, v41, 0x3dd53b94, v50
	v_fmamk_f32 v42, v42, 0x3dd53b94, v50
	v_fmamk_f32 v43, v43, 0x3dd53b94, v50
	v_fmamk_f32 v44, v44, 0x3dd53b94, v50
	v_fmamk_f32 v45, v45, 0x3dd53b94, v50
	v_fmamk_f32 v46, v46, 0x3dd53b94, v50
	v_fmamk_f32 v47, v47, 0x3dd53b94, v50
	v_fmamk_f32 v48, v48, 0x3dd53b94, v50
	v_fmamk_f32 v49, v49, 0x3dd53b94, v50
	v_or3_b32 v34, v35, v36, v34
	s_cselect_b32 s1, 0, 0
	v_exp_f32_e32 v230, v37
	v_exp_f32_e32 v226, v38
	v_exp_f32_e32 v228, v39
	v_exp_f32_e32 v224, v40
	v_exp_f32_e32 v225, v41
	v_exp_f32_e32 v221, v42
	v_exp_f32_e32 v223, v43
	v_exp_f32_e32 v220, v44
	v_exp_f32_e32 v222, v45
	v_exp_f32_e32 v217, v46
	v_exp_f32_e32 v219, v47
	v_exp_f32_e32 v216, v48
	v_exp_f32_e32 v218, v49
	v_add_u32_e32 v200, s1, v34
	s_and_b32 s1, s84, 7
	s_lshl_b32 s1, s1, 9
	s_waitcnt vmcnt(0)
	v_pk_fma_f32 v[146:147], v[32:33], s[34:35], v[50:51] op_sel_hi:[1,0,0]
	v_pk_fma_f32 v[148:149], v[30:31], s[34:35], v[50:51] op_sel_hi:[1,0,0]
	v_pk_fma_f32 v[150:151], v[28:29], s[34:35], v[50:51] op_sel_hi:[1,0,0]
	v_pk_fma_f32 v[152:153], v[26:27], s[34:35], v[50:51] op_sel_hi:[1,0,0]
	v_pk_fma_f32 v[154:155], v[24:25], s[34:35], v[50:51] op_sel_hi:[1,0,0]
	v_pk_fma_f32 v[156:157], v[22:23], s[34:35], v[50:51] op_sel_hi:[1,0,0]
	v_pk_fma_f32 v[162:163], v[20:21], s[34:35], v[50:51] op_sel_hi:[1,0,0]
	v_pk_fma_f32 v[164:165], v[18:19], s[34:35], v[50:51] op_sel_hi:[1,0,0]
	v_lshl_add_u32 v170, v168, 2, v51
	v_lshl_add_u32 v158, v52, 2, v51
	s_add_u32 s20, s4, s1
	v_mov_b64_e32 v[64:65], v[16:17]
	v_mov_b64_e32 v[48:49], v[16:17]
	v_mov_b64_e32 v[32:33], v[16:17]
	s_mov_b32 s17, 1
	s_mov_b32 s0, 0
	v_cmp_gt_u32_e64 s[2:3], 32, v161
	s_mov_b32 s19, 2
	s_addc_u32 s21, s5, 0
	v_mov_b32_e32 v171, 0
	v_mov_b64_e32 v[62:63], v[14:15]
	v_mov_b64_e32 v[60:61], v[12:13]
	v_mov_b64_e32 v[58:59], v[10:11]
	v_mov_b64_e32 v[56:57], v[8:9]
	v_mov_b64_e32 v[54:55], v[6:7]
	v_mov_b64_e32 v[52:53], v[4:5]
	v_mov_b64_e32 v[50:51], v[2:3]
	v_mov_b64_e32 v[46:47], v[14:15]
	v_mov_b64_e32 v[44:45], v[12:13]
	v_mov_b64_e32 v[42:43], v[10:11]
	v_mov_b64_e32 v[40:41], v[8:9]
	v_mov_b64_e32 v[38:39], v[6:7]
	v_mov_b64_e32 v[36:37], v[4:5]
	v_mov_b64_e32 v[34:35], v[2:3]
	v_mov_b64_e32 v[30:31], v[14:15]
	v_mov_b64_e32 v[28:29], v[12:13]
	v_mov_b64_e32 v[26:27], v[10:11]
	v_mov_b64_e32 v[24:25], v[8:9]
	v_mov_b64_e32 v[22:23], v[6:7]
	v_mov_b64_e32 v[20:21], v[4:5]
	v_mov_b64_e32 v[18:19], v[2:3]
	s_mov_b32 s22, 2
	s_waitcnt vmcnt(0)
	s_barrier
	v_mov_b32_e32 v245, v172
	v_ashrrev_i32_e32 v250, 4, v245
	v_xor_b32_e32 v246, v250, v245
	v_lshlrev_b32_e32 v246, 3, v246
	v_lshrrev_b32_e32 v247, 1, v245
	v_and_b32_e32 v246, 0x78, v246
	v_and_b32_e32 v255, 8, v247
	v_lshrrev_b32_e32 v247, 1, v250
	v_bfe_u32 v254, v245, 2, 2
	v_and_b32_e32 v248, 4, v247
	v_lshl_or_b32 v246, v250, 11, v246
	v_and_or_b32 v250, v250, s75, v255
	v_lshlrev_b32_e32 v247, 3, v245
	v_or3_b32 v250, v250, v248, v254
	v_and_b32_e32 v251, 0x60, v245
	v_and_b32_e32 v249, 24, v247
	v_lshlrev_b32_e32 v250, 11, v250
	v_or3_b32 v250, v250, v251, v249
	v_ashrrev_i32_e32 v247, 31, v246
	v_ashrrev_i32_e32 v251, 31, v250
	v_lshlrev_b64 v[246:247], 1, v[246:247]
	v_lshlrev_b64 v[248:249], 1, v[250:251]
	v_lshrrev_b32_e32 v255, 4, v245
	v_lshrrev_b32_e32 v254, 3, v245
	v_xor_b32_e32 v255, v255, v245
	v_mul_lo_u32 v254, v254, s76
	v_lshlrev_b32_e32 v255, 3, v255
	v_and_or_b32 v254, v255, 56, v254
	v_ashrrev_i32_e32 v255, 31, v254
	v_lshlrev_b64 v[250:251], 1, v[254:255]
.LBB0_543:
	s_mov_b32 s23, s17
	s_mov_b32 s17, s0
	s_add_i32 s71, 0, 0x10000
	v_add_u32_e32 v203, s71, v173
	ds_read_b128 v[66:69], v203
	ds_read_b128 v[70:73], v203 offset:8192
	v_add_u32_e32 v204, s71, v175
	ds_read_b128 v[206:209], v204
	ds_read_b128 v[210:213], v204 offset:8192
	v_add_u32_e32 v205, s71, v177
	s_waitcnt lgkmcnt(0)
	v_mfma_f32_32x32x16_bf16 v[82:97], v[66:69], v[142:145], 0
	s_add_i32 s0, 0, 0x16000
	v_exp_f32_e32 v240, v146
	v_add_f32_e32 v146, 0, v229
	v_add_f32_e32 v146, v231, v146
	v_add_f32_e32 v146, v227, v146
	v_add_f32_e32 v146, v230, v146
	v_add_f32_e32 v146, v226, v146
	v_mfma_f32_32x32x16_bf16 v[66:81], v[70:73], v[142:145], 0
	v_add_f32_e32 v146, v228, v146
	v_add_f32_e32 v146, v224, v146
	v_add_f32_e32 v146, v225, v146
	v_add_f32_e32 v146, v221, v146
	v_add_f32_e32 v146, v223, v146
	v_add_f32_e32 v146, v220, v146
	v_add_f32_e32 v146, v222, v146
	v_mfma_f32_32x32x16_bf16 v[82:97], v[206:209], v[138:141], v[82:97]
	v_exp_f32_e32 v164, v164
	v_add_f32_e32 v146, v217, v146
	v_exp_f32_e32 v165, v165
	v_add_f32_e32 v146, v219, v146
	v_exp_f32_e32 v197, v162
	v_add_f32_e32 v146, v216, v146
	v_add_f32_e32 v146, v218, v146
	v_mfma_f32_32x32x16_bf16 v[66:81], v[210:213], v[138:141], v[66:81]
	ds_read_b128 v[206:209], v205
	ds_read_b128 v[210:213], v205 offset:8192
	s_add_u32 s4, s38, s20
	s_addc_u32 s5, s39, s21
	s_add_u32 s24, s4, 0x149ec400
	s_addc_u32 s25, s5, 0
	s_mov_b32 m0, s90
	v_lshl_add_u64 v[254:255], v[246:247], 0, s[24:25]
	s_lshl_b32 s18, s22, 14
	global_load_lds_dwordx4 v[254:255], off
	s_add_u32 s24, s4, 0x14a0c400
	s_addc_u32 s25, s5, 0
	s_mov_b32 m0, s91
	v_lshl_add_u64 v[254:255], v[246:247], 0, s[24:25]
	s_add_i32 s1, s89, s18
	global_load_lds_dwordx4 v[254:255], off
	s_add_u32 s24, s4, 0x149ec500
	s_addc_u32 s25, s5, 0
	s_mov_b32 m0, s1
	v_lshl_add_u64 v[254:255], v[248:249], 0, s[24:25]
	global_load_lds_dwordx4 v[254:255], off
	s_add_u32 s24, s4, 0x14a0c500
	s_addc_u32 s25, s5, 0
	s_add_i32 m0, s1, 0x2000
	v_lshl_add_u64 v[254:255], v[248:249], 0, s[24:25]
	global_load_lds_dwordx4 v[254:255], off
	s_add_u32 s4, s38, s88
	s_addc_u32 s5, s39, s87
	s_add_u32 s4, s4, s36
	s_addc_u32 s5, s5, s37
	s_mov_b32 m0, s92
	v_lshl_add_u64 v[254:255], v[250:251], 0, s[4:5]
	global_load_lds_dwordx4 v[254:255], off
	v_exp_f32_e32 v156, v156
	v_add_f32_e32 v146, v164, v146
	v_exp_f32_e32 v157, v157
	v_add_f32_e32 v146, v165, v146
	v_add_f32_e32 v146, v197, v146
	v_exp_f32_e32 v241, v147
	s_waitcnt lgkmcnt(0)
	v_mfma_f32_32x32x16_bf16 v[82:97], v[206:209], v[134:137], v[82:97]
	v_add_u32_e32 v206, s71, v179
	v_add_u32_e32 v207, s71, v181
	v_mfma_f32_32x32x16_bf16 v[66:81], v[210:213], v[134:137], v[66:81]
	ds_read_b128 v[208:211], v206
	ds_read_b128 v[212:215], v206 offset:8192
	s_waitcnt lgkmcnt(0)
	v_mfma_f32_32x32x16_bf16 v[82:97], v[208:211], v[130:133], v[82:97]
	v_mfma_f32_32x32x16_bf16 v[66:81], v[212:215], v[130:133], v[66:81]
	ds_read_b128 v[208:211], v207
	ds_read_b128 v[212:215], v207 offset:8192
	s_waitcnt lgkmcnt(0)
	v_mfma_f32_32x32x16_bf16 v[82:97], v[208:211], v[126:129], v[82:97]
	v_add_u32_e32 v208, s71, v183
	v_add_u32_e32 v209, s71, v187
	v_mfma_f32_32x32x16_bf16 v[66:81], v[212:215], v[126:129], v[66:81]
	ds_read_b128 v[210:213], v208
	ds_read_b128 v[232:235], v208 offset:8192
	s_waitcnt lgkmcnt(0)
	v_mfma_f32_32x32x16_bf16 v[82:97], v[210:213], v[122:125], v[82:97]
	v_mfma_f32_32x32x16_bf16 v[66:81], v[232:235], v[122:125], v[66:81]
	ds_read_b128 v[210:213], v209
	ds_read_b128 v[232:235], v209 offset:8192
	s_waitcnt lgkmcnt(0)
	v_mfma_f32_32x32x16_bf16 v[82:97], v[210:213], v[118:121], v[82:97]
	v_add_u32_e32 v210, s71, v189
	v_add_u32_e32 v211, s0, v191
	v_mfma_f32_32x32x16_bf16 v[66:81], v[232:235], v[118:121], v[66:81]
	ds_read_b128 v[212:215], v210
	ds_read_b128 v[232:235], v210 offset:8192
	s_waitcnt lgkmcnt(0)
	v_mfma_f32_32x32x16_bf16 v[82:97], v[212:215], v[114:117], v[82:97]
	v_mfma_f32_32x32x16_bf16 v[66:81], v[232:235], v[114:117], v[66:81]
	ds_read_b128 v[212:215], v211
	ds_read_b128 v[232:235], v211 offset:4096
	s_waitcnt lgkmcnt(0)
	v_mfma_f32_32x32x16_bf16 v[82:97], v[212:215], v[110:113], v[82:97]
	v_add_u32_e32 v212, s0, v193
	v_add_u32_e32 v213, s0, v195
	v_add_u32_e32 v214, s0, v198
	v_exp_f32_e32 v215, v163
	s_nop 0
	v_add_f32_e32 v146, v215, v146
	v_mfma_f32_32x32x16_bf16 v[66:81], v[232:235], v[110:113], v[66:81]
	ds_read_b128 v[232:235], v212
	ds_read_b128 v[236:239], v212 offset:4096
	v_add_f32_e32 v146, v156, v146
	v_add_f32_e32 v146, v157, v146
	s_waitcnt lgkmcnt(0)
	v_mfma_f32_32x32x16_bf16 v[82:97], v[232:235], v[106:109], v[82:97]
	v_mfma_f32_32x32x16_bf16 v[66:81], v[236:239], v[106:109], v[66:81]
	ds_read_b128 v[232:235], v213
	ds_read_b128 v[236:239], v213 offset:4096
	s_waitcnt lgkmcnt(0)
	v_mfma_f32_32x32x16_bf16 v[82:97], v[232:235], v[102:105], v[82:97]
	v_mfma_f32_32x32x16_bf16 v[66:81], v[236:239], v[102:105], v[66:81]
	ds_read_b128 v[232:235], v214
	ds_read_b128 v[236:239], v214 offset:4096
	s_waitcnt lgkmcnt(0)
	v_mfma_f32_32x32x16_bf16 v[82:97], v[232:235], v[98:101], v[82:97]
	v_exp_f32_e32 v232, v154
	v_exp_f32_e32 v233, v155
	v_exp_f32_e32 v234, v152
	v_exp_f32_e32 v235, v153
	v_add_f32_e32 v146, v232, v146
	v_add_f32_e32 v146, v233, v146
	v_add_f32_e32 v146, v234, v146
	v_mfma_f32_32x32x16_bf16 v[66:81], v[236:239], v[98:101], v[66:81]
	v_exp_f32_e32 v236, v150
	v_exp_f32_e32 v237, v151
	v_exp_f32_e32 v238, v148
	v_exp_f32_e32 v239, v149
	v_add_f32_e32 v146, v235, v146
	v_add_f32_e32 v146, v236, v146
	v_add_f32_e32 v146, v237, v146
	v_add_f32_e32 v146, v238, v146
	v_add_f32_e32 v146, v239, v146
	v_add_f32_e32 v146, v240, v146
	v_add_f32_e32 v162, v241, v146
	v_mov_b32_e32 v163, v162
	s_nop 1
	v_permlane32_swap_b32_e32 v162, v163
	v_cvt_pk_bf16_f32 v146, v229, v231
	v_cvt_pk_bf16_f32 v147, v227, v230
	v_cvt_pk_bf16_f32 v148, v226, v228
	v_cvt_pk_bf16_f32 v149, v224, v225
	v_cvt_pk_bf16_f32 v150, v221, v223
	v_cvt_pk_bf16_f32 v151, v220, v222
	v_cvt_pk_bf16_f32 v152, v217, v219
	v_cvt_pk_bf16_f32 v153, v216, v218
	v_cvt_pk_bf16_f32 v154, v164, v165
	v_cvt_pk_bf16_f32 v155, v197, v215
	v_cvt_pk_bf16_f32 v156, v156, v157
	v_cvt_pk_bf16_f32 v157, v232, v233
	v_cvt_pk_bf16_f32 v216, v234, v235
	v_cvt_pk_bf16_f32 v217, v236, v237
	v_cvt_pk_bf16_f32 v218, v238, v239
	v_cvt_pk_bf16_f32 v219, v240, v241
	s_nop 0
	v_permlane32_swap_b32_e32 v146, v148
	v_permlane32_swap_b32_e32 v147, v149
	v_permlane32_swap_b32_e32 v150, v152
	v_permlane32_swap_b32_e32 v151, v153
	v_permlane32_swap_b32_e32 v154, v156
	v_permlane32_swap_b32_e32 v155, v157
	v_permlane32_swap_b32_e32 v216, v218
	v_permlane32_swap_b32_e32 v217, v219
	s_lshl_b32 s24, s17, 14
	v_add_u32_e32 v197, s24, v200
	ds_read_b64_tr_b16 v[220:221], v197 offset:0
	ds_read_b64_tr_b16 v[222:223], v197 offset:0x800
	ds_read_b64_tr_b16 v[224:225], v197 offset:0x1000
	ds_read_b64_tr_b16 v[226:227], v197 offset:0x1800
	ds_read_b64_tr_b16 v[228:229], v197 offset:0x2000
	ds_read_b64_tr_b16 v[230:231], v197 offset:0x2800
	ds_read_b64_tr_b16 v[232:233], v197 offset:0x3000
	ds_read_b64_tr_b16 v[234:235], v197 offset:0x3800
	s_waitcnt lgkmcnt(0)
	s_nop 0
	v_mfma_f32_32x32x16_bf16 v[2:17], v[146:149], v[220:223], v[2:17]
	ds_read_b64_tr_b16 v[220:221], v197 offset:0x200
	ds_read_b64_tr_b16 v[222:223], v197 offset:0xa00
	v_max_f32_e32 v164, v83, v83
	v_max_f32_e32 v165, v82, v82
	v_max_f32_e32 v164, v165, v164
	v_max3_f32 v164, v164, v84, v85
	v_max3_f32 v164, v164, v86, v87
	v_mfma_f32_32x32x16_bf16 v[2:17], v[150:153], v[224:227], v[2:17]
	ds_read_b64_tr_b16 v[224:225], v197 offset:0x1200
	ds_read_b64_tr_b16 v[226:227], v197 offset:0x1a00
	v_max3_f32 v164, v164, v88, v89
	v_max3_f32 v164, v164, v90, v91
	v_max3_f32 v164, v164, v92, v93
	v_max3_f32 v164, v164, v94, v95
	v_max3_f32 v164, v164, v96, v97
	v_mfma_f32_32x32x16_bf16 v[2:17], v[154:157], v[228:231], v[2:17]
	ds_read_b64_tr_b16 v[228:229], v197 offset:0x2200
	ds_read_b64_tr_b16 v[230:231], v197 offset:0x2a00
	ds_read_b64_tr_b16 v[236:237], v197 offset:0x3200
	ds_read_b64_tr_b16 v[238:239], v197 offset:0x3a00
	s_waitcnt lgkmcnt(0)
	v_mfma_f32_32x32x16_bf16 v[2:17], v[216:219], v[232:235], v[2:17]
	v_mfma_f32_32x32x16_bf16 v[50:65], v[146:149], v[220:223], v[50:65]
	v_max3_f32 v164, v164, v66, v67
	v_max3_f32 v164, v164, v68, v69
	v_max3_f32 v164, v164, v70, v71
	v_max3_f32 v164, v164, v72, v73
	v_max3_f32 v164, v164, v74, v75
	v_max3_f32 v164, v164, v76, v77
	v_max3_f32 v164, v164, v78, v79
	v_mfma_f32_32x32x16_bf16 v[50:65], v[150:153], v[224:227], v[50:65]
	v_max3_f32 v164, v164, v80, v81
	v_mov_b32_e32 v165, v164
	s_nop 1
	v_permlane32_swap_b32_e32 v164, v165
	ds_read_b64_tr_b16 v[220:221], v197 offset:0x400
	v_max_f32_e32 v165, v165, v165
	v_max_f32_e32 v164, v164, v164
	v_mfma_f32_32x32x16_bf16 v[50:65], v[154:157], v[228:231], v[50:65]
	ds_read_b64_tr_b16 v[222:223], v197 offset:0xc00
	v_max_f32_e32 v164, v164, v165
	v_max_f32_e32 v165, v202, v202
	ds_read_b64_tr_b16 v[224:225], v197 offset:0x1400
	v_max_f32_e32 v165, v165, v164
	ds_read_b64_tr_b16 v[226:227], v197 offset:0x1c00
	v_sub_f32_e32 v215, v164, v202
	v_mfma_f32_32x32x16_bf16 v[50:65], v[216:219], v[236:239], v[50:65]
	v_sub_f32_e32 v164, v202, v165
	ds_read_b64_tr_b16 v[228:229], v197 offset:0x2400
	v_mul_f32_e32 v164, 0x3dd53b94, v164
	ds_read_b64_tr_b16 v[230:231], v197 offset:0x2c00
	v_exp_f32_e32 v164, v164
	ds_read_b64_tr_b16 v[232:233], v197 offset:0x3400
	v_cmp_ge_f32_e32 vcc, s77, v215
	ds_read_b64_tr_b16 v[234:235], v197 offset:0x3c00
	s_cmp_eq_u64 vcc, exec
	s_waitcnt lgkmcnt(0)
	s_cselect_b64 s[4:5], -1, 0
	v_cndmask_b32_e64 v164, v164, 1.0, s[4:5]
	v_mfma_f32_32x32x16_bf16 v[34:49], v[146:149], v[220:223], v[34:49]
	ds_read_b64_tr_b16 v[220:221], v197 offset:0x600
	ds_read_b64_tr_b16 v[222:223], v197 offset:0xe00
	v_mfma_f32_32x32x16_bf16 v[34:49], v[150:153], v[224:227], v[34:49]
	ds_read_b64_tr_b16 v[224:225], v197 offset:0x1600
	ds_read_b64_tr_b16 v[226:227], v197 offset:0x1e00
	v_mfma_f32_32x32x16_bf16 v[34:49], v[154:157], v[228:231], v[34:49]
	ds_read_b64_tr_b16 v[228:229], v197 offset:0x2600
	ds_read_b64_tr_b16 v[230:231], v197 offset:0x2e00
	ds_read_b64_tr_b16 v[236:237], v197 offset:0x3600
	ds_read_b64_tr_b16 v[238:239], v197 offset:0x3e00
	s_waitcnt lgkmcnt(0)
	v_mfma_f32_32x32x16_bf16 v[34:49], v[216:219], v[232:235], v[34:49]
	v_mfma_f32_32x32x16_bf16 v[18:33], v[146:149], v[220:223], v[18:33]
	v_cmp_gt_f32_e32 vcc, 1.0, v164
	v_mfma_f32_32x32x16_bf16 v[18:33], v[150:153], v[224:227], v[18:33]
	v_mfma_f32_32x32x16_bf16 v[18:33], v[154:157], v[228:231], v[18:33]
	v_mfma_f32_32x32x16_bf16 v[18:33], v[216:219], v[236:239], v[18:33]
	s_cbranch_vccz .LBB0_547
	s_and_saveexec_b64 s[0:1], s[2:3]
	ds_write_b32 v170, v164 offset:128
	s_or_b64 exec, exec, s[0:1]
	s_waitcnt lgkmcnt(0)
	ds_read_b128 v[146:149], v158 offset:224
	ds_read_b128 v[150:153], v158 offset:192
	ds_read_b128 v[154:157], v158 offset:160
	ds_read_b128 v[216:219], v158 offset:128
	s_waitcnt lgkmcnt(0)
	v_pk_mul_f32 v[16:17], v[16:17], v[148:149]
	v_pk_mul_f32 v[12:13], v[12:13], v[152:153]
	v_pk_mul_f32 v[8:9], v[8:9], v[156:157]
	v_pk_mul_f32 v[4:5], v[4:5], v[218:219]
	v_pk_mul_f32 v[14:15], v[14:15], v[146:147]
	v_pk_mul_f32 v[10:11], v[10:11], v[150:151]
	v_pk_mul_f32 v[6:7], v[6:7], v[154:155]
	v_pk_mul_f32 v[2:3], v[2:3], v[216:217]
	v_pk_mul_f32 v[64:65], v[64:65], v[148:149]
	v_pk_mul_f32 v[60:61], v[60:61], v[152:153]
	v_pk_mul_f32 v[56:57], v[56:57], v[156:157]
	v_pk_mul_f32 v[52:53], v[52:53], v[218:219]
	v_pk_mul_f32 v[62:63], v[62:63], v[146:147]
	v_pk_mul_f32 v[58:59], v[58:59], v[150:151]
	v_pk_mul_f32 v[54:55], v[54:55], v[154:155]
	v_pk_mul_f32 v[50:51], v[50:51], v[216:217]
	v_pk_mul_f32 v[48:49], v[48:49], v[148:149]
	v_pk_mul_f32 v[44:45], v[44:45], v[152:153]
	v_pk_mul_f32 v[40:41], v[40:41], v[156:157]
	v_pk_mul_f32 v[36:37], v[36:37], v[218:219]
	v_pk_mul_f32 v[46:47], v[46:47], v[146:147]
	v_pk_mul_f32 v[42:43], v[42:43], v[150:151]
	v_pk_mul_f32 v[38:39], v[38:39], v[154:155]
	v_pk_mul_f32 v[34:35], v[34:35], v[216:217]
	v_pk_mul_f32 v[32:33], v[32:33], v[148:149]
	v_pk_mul_f32 v[28:29], v[28:29], v[152:153]
	v_pk_mul_f32 v[24:25], v[24:25], v[156:157]
	v_pk_mul_f32 v[20:21], v[20:21], v[218:219]
	v_pk_mul_f32 v[30:31], v[30:31], v[146:147]
	v_pk_mul_f32 v[26:27], v[26:27], v[150:151]
	v_pk_mul_f32 v[22:23], v[22:23], v[154:155]
	v_pk_mul_f32 v[18:19], v[18:19], v[216:217]

.LBB0_549:
	v_cndmask_b32_e64 v165, v165, v202, s[4:5]
	v_mul_f32_e32 v154, 0xbdd53b94, v165
	v_fmamk_f32 v82, v82, 0x3dd53b94, v154
	v_fmamk_f32 v83, v83, 0x3dd53b94, v154
	v_fmamk_f32 v84, v84, 0x3dd53b94, v154
	v_fmamk_f32 v85, v85, 0x3dd53b94, v154
	v_fmamk_f32 v86, v86, 0x3dd53b94, v154
	v_fmamk_f32 v87, v87, 0x3dd53b94, v154
	v_fmamk_f32 v88, v88, 0x3dd53b94, v154
	v_fmamk_f32 v89, v89, 0x3dd53b94, v154
	v_fmamk_f32 v90, v90, 0x3dd53b94, v154
	v_fmamk_f32 v91, v91, 0x3dd53b94, v154
	v_fmamk_f32 v92, v92, 0x3dd53b94, v154
	v_fmamk_f32 v93, v93, 0x3dd53b94, v154
	v_fmamk_f32 v94, v94, 0x3dd53b94, v154
	v_fmamk_f32 v95, v95, 0x3dd53b94, v154
	v_fmamk_f32 v96, v96, 0x3dd53b94, v154
	v_fmamk_f32 v97, v97, 0x3dd53b94, v154
	v_fmamk_f32 v202, v69, 0x3dd53b94, v154
	v_fmamk_f32 v215, v70, 0x3dd53b94, v154
	v_fmamk_f32 v232, v79, 0x3dd53b94, v154
	v_fmamk_f32 v233, v80, 0x3dd53b94, v154
	v_fmamk_f32 v155, v66, 0x3dd53b94, v154
	v_fmamk_f32 v156, v67, 0x3dd53b94, v154
	v_fmamk_f32 v157, v68, 0x3dd53b94, v154
	v_fmamk_f32 v216, v71, 0x3dd53b94, v154
	v_fmamk_f32 v217, v72, 0x3dd53b94, v154
	v_fmamk_f32 v218, v73, 0x3dd53b94, v154
	v_fmamk_f32 v219, v74, 0x3dd53b94, v154
	v_fmamk_f32 v220, v75, 0x3dd53b94, v154
	v_fmamk_f32 v221, v76, 0x3dd53b94, v154
	v_fmamk_f32 v222, v77, 0x3dd53b94, v154
	v_fmamk_f32 v223, v78, 0x3dd53b94, v154
	v_exp_f32_e32 v224, v82
	v_exp_f32_e32 v225, v83
	v_exp_f32_e32 v226, v84
	v_exp_f32_e32 v227, v85
	v_exp_f32_e32 v228, v86
	v_exp_f32_e32 v229, v87
	v_exp_f32_e32 v230, v88
	v_exp_f32_e32 v231, v89
	v_exp_f32_e32 v234, v90
	v_exp_f32_e32 v235, v91
	v_exp_f32_e32 v236, v92
	v_exp_f32_e32 v237, v93
	v_exp_f32_e32 v238, v94
	v_exp_f32_e32 v239, v95
	v_exp_f32_e32 v240, v96
	v_exp_f32_e32 v241, v97
	v_fmac_f32_e32 v154, 0x3dd53b94, v81
	ds_read_b128 v[66:69], v174 offset:49152
	ds_read_b128 v[70:73], v174 offset:57344
	ds_read_b128 v[146:149], v176 offset:49152
	ds_read_b128 v[150:153], v176 offset:57344
	v_exp_f32_e32 v155, v155
	v_exp_f32_e32 v156, v156
	s_waitcnt lgkmcnt(0)
	v_mfma_f32_32x32x16_bf16 v[82:97], v[66:69], v[142:145], 0
	v_exp_f32_e32 v157, v157
	v_exp_f32_e32 v202, v202
	v_exp_f32_e32 v215, v215
	v_exp_f32_e32 v216, v216
	v_exp_f32_e32 v217, v217
	v_exp_f32_e32 v218, v218
	v_exp_f32_e32 v219, v219
	v_mfma_f32_32x32x16_bf16 v[66:81], v[70:73], v[142:145], 0
	v_exp_f32_e32 v220, v220
	v_exp_f32_e32 v221, v221
	v_exp_f32_e32 v222, v222
	v_exp_f32_e32 v223, v223
	v_exp_f32_e32 v242, v232
	v_exp_f32_e32 v243, v233
	v_exp_f32_e32 v244, v154
	v_mfma_f32_32x32x16_bf16 v[82:97], v[146:149], v[138:141], v[82:97]
	v_mfma_f32_32x32x16_bf16 v[66:81], v[150:153], v[138:141], v[66:81]
	ds_read_b128 v[146:149], v178 offset:49152
	ds_read_b128 v[150:153], v178 offset:57344
	s_cmp_lg_u32 s98, 0
	s_cbranch_scc1 .Lattn_mla_nopf
	s_add_u32 s0, s38, s20
	s_addc_u32 s1, s39, s21
	s_add_u32 s100, s0, s42
	s_addc_u32 s101, s1, s43
	s_mov_b32 m0, s93
	v_lshl_add_u64 v[254:255], v[246:247], 0, s[100:101]
	global_load_lds_dwordx4 v[254:255], off
	s_add_u32 s100, s0, s46
	s_addc_u32 s101, s1, s47
	s_mov_b32 m0, s94
	v_lshl_add_u64 v[254:255], v[246:247], 0, s[100:101]
	global_load_lds_dwordx4 v[254:255], off
	s_add_u32 s100, s0, s44
	s_addc_u32 s101, s1, s45
	s_add_i32 s98, s89, s24
	s_mov_b32 m0, s98
	v_lshl_add_u64 v[254:255], v[248:249], 0, s[100:101]
	global_load_lds_dwordx4 v[254:255], off
	s_add_u32 s100, s0, s50
	s_addc_u32 s101, s1, s51
	s_add_i32 m0, s98, 0x2000
	v_lshl_add_u64 v[254:255], v[248:249], 0, s[100:101]
	global_load_lds_dwordx4 v[254:255], off
	s_add_u32 s0, s38, s88
	s_addc_u32 s1, s39, s87
	s_add_u32 s0, s0, s58
	s_addc_u32 s1, s1, s59
	s_mov_b32 m0, s95
	v_lshl_add_u64 v[254:255], v[250:251], 0, s[0:1]
	global_load_lds_dwordx4 v[254:255], off
